# plus: conv_caches 4-way batched, stray prologue drains removed in all GEMM instances, attention task barrier no longer drains output stores
# speedup vs baseline: 1.0169x; 1.0005x over previous
.LBB0_64:
	s_add_u32 s44, s72, 0x1000
	s_addc_u32 s45, s73, 0
	s_add_u32 s46, s72, 0x50000
	s_addc_u32 s47, s73, 0
	v_bfe_u32 v168, v206, 4, 2
	s_add_u32 s48, s72, 0x549800
	v_and_b32_e32 v165, 15, v206
	v_lshlrev_b32_e32 v16, 4, v168
	v_lshlrev_b32_e32 v17, 2, v206
	s_addc_u32 s49, s73, 0
	s_lshl_b32 s17, s6, 6
	v_lshl_or_b32 v16, v165, 6, v16
	s_lshl_b32 s6, s6, 13
	v_and_b32_e32 v17, 32, v17
	v_bitop3_b32 v18, v16, s6, v17 bitop3:0xde
	s_lshl_b32 s6, s7, 5
	s_and_b32 s18, s6, 0x60
	s_add_i32 m0, s13, 0x18000
	v_lshl_add_u64 v[8:9], v[8:9], 0, s[96:97]
	s_lshl_b32 s6, s18, 7
	s_waitcnt vmcnt(2)
	s_barrier
	global_load_lds_dwordx4 v[8:9], off
	v_lshl_add_u64 v[6:7], v[6:7], 0, s[96:97]
	s_add_i32 m0, s13, 0x1a000
	s_add_i32 s19, s13, 0x8000
	s_add_i32 s20, s13, 0xa000
	v_bitop3_b32 v169, s6, v16, v17 bitop3:0xf6
	global_load_lds_dwordx4 v[6:7], off
	v_lshl_add_u64 v[2:3], v[2:3], 0, s[96:97]
	s_mov_b32 m0, s19
	s_add_u32 s6, s4, 0x40080
	global_load_lds_dwordx4 v[2:3], off
	v_lshl_add_u64 v[2:3], v[4:5], 0, s[96:97]
	s_mov_b32 m0, s20
	s_addc_u32 s7, s5, 0
	global_load_lds_dwordx4 v[2:3], off
	s_add_i32 m0, s13, 0x1c000
	v_lshl_add_u64 v[2:3], s[6:7], 0, v[0:1]
	global_load_lds_dwordx4 v[2:3], off
	v_lshl_add_u64 v[2:3], s[6:7], 0, v[150:151]
	s_add_i32 m0, s13, 0x1e000
	s_cmpk_lt_u32 s21, 0x100
	global_load_lds_dwordx4 v[2:3], off
	v_lshlrev_b32_e32 v2, 14, v10
	v_and_b32_e32 v2, 0xffff8000, v2
	v_lshl_add_u32 v2, v11, 11, v2
	v_and_b32_e32 v3, 1, v10
	v_lshl_or_b32 v2, v3, 6, v2
	v_lshl_add_u32 v152, v12, 1, v2
	v_lshlrev_b32_e32 v2, 14, v13
	v_and_b32_e32 v2, 0xffff8000, v2
	s_waitcnt vmcnt(6)
	s_cselect_b64 s[50:51], -1, 0
	s_ashr_i32 s21, s85, 31
	s_ashr_i32 s22, s84, 31
	s_and_b32 s6, s85, 7
	v_lshl_add_u32 v2, v14, 11, v2
	v_and_b32_e32 v3, 1, v13
	s_cmp_eq_u32 s6, 0
	v_lshl_or_b32 v2, v3, 6, v2
	s_mov_b32 s23, 0
	s_cselect_b64 s[52:53], -1, 0
	v_mov_b32_e32 v153, v1
	v_lshl_add_u32 v154, v15, 1, v2
	v_mov_b32_e32 v155, v1
	v_add_u32_e32 v170, 0, v18
	s_mov_b64 s[58:59], s[0:1]
	s_mov_b64 s[60:61], s[4:5]
	s_barrier
	s_branch .LBB0_67

.LBB0_146:
	s_add_u32 s0, s0, 0x40080
	s_addc_u32 s1, s1, 0
	s_add_u32 s2, s4, 0x100
	v_mov_b32_e32 v2, 0
	s_addc_u32 s3, s5, 0
	s_mov_b32 s8, -2
	v_mov_b32_e32 v3, v2
	v_mov_b32_e32 v4, v2
	v_mov_b32_e32 v5, v2
	v_mov_b32_e32 v6, v2
	v_mov_b32_e32 v7, v2
	v_mov_b32_e32 v8, v2
	v_mov_b32_e32 v9, v2
	v_mov_b32_e32 v18, v2
	v_mov_b32_e32 v19, v2
	v_mov_b32_e32 v20, v2
	v_mov_b32_e32 v21, v2
	v_mov_b32_e32 v22, v2
	v_mov_b32_e32 v23, v2
	v_mov_b32_e32 v24, v2
	v_mov_b32_e32 v25, v2
	v_mov_b32_e32 v34, v2
	v_mov_b32_e32 v35, v2
	v_mov_b32_e32 v36, v2
	v_mov_b32_e32 v37, v2
	v_mov_b32_e32 v38, v2
	v_mov_b32_e32 v39, v2
	v_mov_b32_e32 v40, v2
	v_mov_b32_e32 v41, v2
	v_mov_b32_e32 v50, v2
	v_mov_b32_e32 v51, v2
	v_mov_b32_e32 v52, v2
	v_mov_b32_e32 v53, v2
	v_mov_b32_e32 v54, v2
	v_mov_b32_e32 v55, v2
	v_mov_b32_e32 v56, v2
	v_mov_b32_e32 v57, v2
	v_mov_b32_e32 v10, v2
	v_mov_b32_e32 v11, v2
	v_mov_b32_e32 v12, v2
	v_mov_b32_e32 v13, v2
	v_mov_b32_e32 v14, v2
	v_mov_b32_e32 v15, v2
	v_mov_b32_e32 v16, v2
	v_mov_b32_e32 v17, v2
	v_mov_b32_e32 v26, v2
	v_mov_b32_e32 v27, v2
	v_mov_b32_e32 v28, v2
	v_mov_b32_e32 v29, v2
	v_mov_b32_e32 v30, v2
	v_mov_b32_e32 v31, v2
	v_mov_b32_e32 v32, v2
	v_mov_b32_e32 v33, v2
	v_mov_b32_e32 v42, v2
	v_mov_b32_e32 v43, v2
	v_mov_b32_e32 v44, v2
	v_mov_b32_e32 v45, v2
	v_mov_b32_e32 v46, v2
	v_mov_b32_e32 v47, v2
	v_mov_b32_e32 v48, v2
	v_mov_b32_e32 v49, v2
	v_mov_b32_e32 v58, v2
	v_mov_b32_e32 v59, v2
	v_mov_b32_e32 v60, v2
	v_mov_b32_e32 v61, v2
	v_mov_b32_e32 v62, v2
	v_mov_b32_e32 v63, v2
	v_mov_b32_e32 v64, v2
	v_mov_b32_e32 v65, v2
	v_mov_b32_e32 v66, v2
	v_mov_b32_e32 v67, v2
	v_mov_b32_e32 v68, v2
	v_mov_b32_e32 v69, v2
	v_mov_b32_e32 v70, v2
	v_mov_b32_e32 v71, v2
	v_mov_b32_e32 v72, v2
	v_mov_b32_e32 v73, v2
	v_mov_b32_e32 v82, v2
	v_mov_b32_e32 v83, v2
	v_mov_b32_e32 v84, v2
	v_mov_b32_e32 v85, v2
	v_mov_b32_e32 v86, v2
	v_mov_b32_e32 v87, v2
	v_mov_b32_e32 v88, v2
	v_mov_b32_e32 v89, v2
	v_mov_b32_e32 v98, v2
	v_mov_b32_e32 v99, v2
	v_mov_b32_e32 v100, v2
	v_mov_b32_e32 v101, v2
	v_mov_b32_e32 v102, v2
	v_mov_b32_e32 v103, v2
	v_mov_b32_e32 v104, v2
	v_mov_b32_e32 v105, v2
	v_mov_b32_e32 v114, v2
	v_mov_b32_e32 v115, v2
	v_mov_b32_e32 v116, v2
	v_mov_b32_e32 v117, v2
	v_mov_b32_e32 v118, v2
	v_mov_b32_e32 v119, v2
	v_mov_b32_e32 v120, v2
	v_mov_b32_e32 v121, v2
	v_mov_b32_e32 v74, v2
	v_mov_b32_e32 v75, v2
	v_mov_b32_e32 v76, v2
	v_mov_b32_e32 v77, v2
	v_mov_b32_e32 v78, v2
	v_mov_b32_e32 v79, v2
	v_mov_b32_e32 v80, v2
	v_mov_b32_e32 v81, v2
	v_mov_b32_e32 v90, v2
	v_mov_b32_e32 v91, v2
	v_mov_b32_e32 v92, v2
	v_mov_b32_e32 v93, v2
	v_mov_b32_e32 v94, v2
	v_mov_b32_e32 v95, v2
	v_mov_b32_e32 v96, v2
	v_mov_b32_e32 v97, v2
	v_mov_b32_e32 v106, v2
	v_mov_b32_e32 v107, v2
	v_mov_b32_e32 v108, v2
	v_mov_b32_e32 v109, v2
	v_mov_b32_e32 v110, v2
	v_mov_b32_e32 v111, v2
	v_mov_b32_e32 v112, v2
	v_mov_b32_e32 v113, v2
	v_mov_b32_e32 v122, v2
	v_mov_b32_e32 v123, v2
	v_mov_b32_e32 v124, v2
	v_mov_b32_e32 v125, v2
	v_mov_b32_e32 v126, v2
	v_mov_b32_e32 v127, v2
	v_mov_b32_e32 v128, v2
	v_mov_b32_e32 v129, v2

.LBB0_459:
	s_add_u32 s33, s4, s18
	s_addc_u32 s36, s5, 0
	s_cmp_gt_i32 s3, 31
	s_cselect_b64 s[8:9], -1, 0
	s_lshl_b32 s10, s3, 4
	s_addk_i32 s10, 0xfe00
	s_ashr_i32 s11, s10, 31
	s_lshl_b64 s[10:11], s[10:11], 2
	s_add_u32 s10, s26, s10
	v_mov_b32_e32 v2, 0
	s_addc_u32 s11, s25, s11
	s_mov_b32 s37, 0
	v_mov_b32_e32 v3, v2
	v_mov_b32_e32 v4, v2
	v_mov_b32_e32 v5, v2
	v_mov_b32_e32 v6, v2
	v_mov_b32_e32 v7, v2
	v_mov_b32_e32 v8, v2
	v_mov_b32_e32 v9, v2
	v_mov_b32_e32 v18, v2
	v_mov_b32_e32 v19, v2
	v_mov_b32_e32 v20, v2
	v_mov_b32_e32 v21, v2
	v_mov_b32_e32 v22, v2
	v_mov_b32_e32 v23, v2
	v_mov_b32_e32 v24, v2
	v_mov_b32_e32 v25, v2
	v_mov_b32_e32 v34, v2
	v_mov_b32_e32 v35, v2
	v_mov_b32_e32 v36, v2
	v_mov_b32_e32 v37, v2
	v_mov_b32_e32 v38, v2
	v_mov_b32_e32 v39, v2
	v_mov_b32_e32 v40, v2
	v_mov_b32_e32 v41, v2
	v_mov_b32_e32 v50, v2
	v_mov_b32_e32 v51, v2
	v_mov_b32_e32 v52, v2
	v_mov_b32_e32 v53, v2
	v_mov_b32_e32 v54, v2
	v_mov_b32_e32 v55, v2
	v_mov_b32_e32 v56, v2
	v_mov_b32_e32 v57, v2
	v_mov_b32_e32 v10, v2
	v_mov_b32_e32 v11, v2
	v_mov_b32_e32 v12, v2
	v_mov_b32_e32 v13, v2
	v_mov_b32_e32 v14, v2
	v_mov_b32_e32 v15, v2
	v_mov_b32_e32 v16, v2
	v_mov_b32_e32 v17, v2
	v_mov_b32_e32 v26, v2
	v_mov_b32_e32 v27, v2
	v_mov_b32_e32 v28, v2
	v_mov_b32_e32 v29, v2
	v_mov_b32_e32 v30, v2
	v_mov_b32_e32 v31, v2
	v_mov_b32_e32 v32, v2
	v_mov_b32_e32 v33, v2
	v_mov_b32_e32 v42, v2
	v_mov_b32_e32 v43, v2
	v_mov_b32_e32 v44, v2
	v_mov_b32_e32 v45, v2
	v_mov_b32_e32 v46, v2
	v_mov_b32_e32 v47, v2
	v_mov_b32_e32 v48, v2
	v_mov_b32_e32 v49, v2
	v_mov_b32_e32 v58, v2
	v_mov_b32_e32 v59, v2
	v_mov_b32_e32 v60, v2
	v_mov_b32_e32 v61, v2
	v_mov_b32_e32 v62, v2
	v_mov_b32_e32 v63, v2
	v_mov_b32_e32 v64, v2
	v_mov_b32_e32 v65, v2
	v_mov_b32_e32 v66, v2
	v_mov_b32_e32 v67, v2
	v_mov_b32_e32 v68, v2
	v_mov_b32_e32 v69, v2
	v_mov_b32_e32 v70, v2
	v_mov_b32_e32 v71, v2
	v_mov_b32_e32 v72, v2
	v_mov_b32_e32 v73, v2
	v_mov_b32_e32 v82, v2
	v_mov_b32_e32 v83, v2
	v_mov_b32_e32 v84, v2
	v_mov_b32_e32 v85, v2
	v_mov_b32_e32 v86, v2
	v_mov_b32_e32 v87, v2
	v_mov_b32_e32 v88, v2
	v_mov_b32_e32 v89, v2
	v_mov_b32_e32 v98, v2
	v_mov_b32_e32 v99, v2
	v_mov_b32_e32 v100, v2
	v_mov_b32_e32 v101, v2
	v_mov_b32_e32 v102, v2
	v_mov_b32_e32 v103, v2
	v_mov_b32_e32 v104, v2
	v_mov_b32_e32 v105, v2
	v_mov_b32_e32 v114, v2
	v_mov_b32_e32 v115, v2
	v_mov_b32_e32 v116, v2
	v_mov_b32_e32 v117, v2
	v_mov_b32_e32 v118, v2
	v_mov_b32_e32 v119, v2
	v_mov_b32_e32 v120, v2
	v_mov_b32_e32 v121, v2
	v_mov_b32_e32 v74, v2
	v_mov_b32_e32 v75, v2
	v_mov_b32_e32 v76, v2
	v_mov_b32_e32 v77, v2
	v_mov_b32_e32 v78, v2
	v_mov_b32_e32 v79, v2
	v_mov_b32_e32 v80, v2
	v_mov_b32_e32 v81, v2
	v_mov_b32_e32 v90, v2
	v_mov_b32_e32 v91, v2
	v_mov_b32_e32 v92, v2
	v_mov_b32_e32 v93, v2
	v_mov_b32_e32 v94, v2
	v_mov_b32_e32 v95, v2
	v_mov_b32_e32 v96, v2
	v_mov_b32_e32 v97, v2
	v_mov_b32_e32 v106, v2
	v_mov_b32_e32 v107, v2
	v_mov_b32_e32 v108, v2
	v_mov_b32_e32 v109, v2
	v_mov_b32_e32 v110, v2
	v_mov_b32_e32 v111, v2
	v_mov_b32_e32 v112, v2
	v_mov_b32_e32 v113, v2
	v_mov_b32_e32 v122, v2
	v_mov_b32_e32 v123, v2
	v_mov_b32_e32 v124, v2
	v_mov_b32_e32 v125, v2
	v_mov_b32_e32 v126, v2
	v_mov_b32_e32 v127, v2
	v_mov_b32_e32 v128, v2
	v_mov_b32_e32 v129, v2
	s_branch .LBB0_463

.LBB0_533:
	v_bfe_u32 v77, v50, 4, 2
	v_and_b32_e32 v76, 15, v50
	v_lshlrev_b32_e32 v16, 4, v77
	v_lshlrev_b32_e32 v17, 2, v50
	s_lshl_b32 s24, s2, 6
	v_lshl_or_b32 v16, v76, 6, v16
	s_lshl_b32 s2, s2, 13
	v_and_b32_e32 v17, 32, v17
	v_bitop3_b32 v18, v16, s2, v17 bitop3:0xde
	s_lshl_b32 s2, s10, 5
	s_and_b32 s2, s2, 0x60
	s_add_i32 m0, s22, 0x18000
	v_lshl_add_u64 v[8:9], v[8:9], 0, s[96:97]
	s_lshl_b32 s10, s2, 7
	s_waitcnt vmcnt(2)
	s_barrier
	global_load_lds_dwordx4 v[8:9], off
	v_lshl_add_u64 v[6:7], v[6:7], 0, s[96:97]
	s_add_i32 m0, s22, 0x1a000
	s_add_i32 s30, s22, 0x8000
	s_add_i32 s33, s22, 0xa000
	v_bitop3_b32 v78, s10, v16, v17 bitop3:0xf6
	global_load_lds_dwordx4 v[6:7], off
	v_lshl_add_u64 v[4:5], v[4:5], 0, s[96:97]
	s_mov_b32 m0, s30
	s_add_u32 s10, s6, 0x40080
	global_load_lds_dwordx4 v[4:5], off
	v_lshl_add_u64 v[2:3], v[2:3], 0, s[96:97]
	s_mov_b32 m0, s33
	s_addc_u32 s11, s7, 0
	global_load_lds_dwordx4 v[2:3], off
	s_add_i32 m0, s22, 0x1c000
	v_lshl_add_u64 v[2:3], s[10:11], 0, v[0:1]
	global_load_lds_dwordx4 v[2:3], off
	v_lshl_add_u64 v[2:3], s[10:11], 0, v[70:71]
	s_add_i32 m0, s22, 0x1e000
	s_lshl_b32 s9, s9, 18
	global_load_lds_dwordx4 v[2:3], off
	s_and_b32 s9, s9, 0x3c00000
	s_lshl_b32 s10, s17, 19
	s_or_b32 s9, s9, s10
	v_readlane_b32 s36, v254, 43
	v_readlane_b32 s37, v254, 44
	s_add_u32 s10, s36, s9
	s_addc_u32 s11, s37, 0
	v_readlane_b32 s12, v252, 1
	v_readlane_b32 s13, v252, 2
	s_add_u32 s34, s12, s10
	s_addc_u32 s35, s13, s11
	v_lshlrev_b32_e32 v2, 14, v10
	v_readlane_b32 s10, v253, 0
	v_and_b32_e32 v2, 0xffff8000, v2
	s_add_u32 s9, s10, s9
	v_readlane_b32 s10, v253, 1
	v_lshl_add_u32 v2, v11, 11, v2
	v_and_b32_e32 v3, 1, v10
	s_addc_u32 s11, s10, 0
	v_lshl_or_b32 v2, v3, 6, v2
	s_add_u32 s10, s9, s36
	v_lshl_add_u32 v2, v12, 1, v2
	v_mov_b32_e32 v3, v1
	s_addc_u32 s11, s11, s37
	v_lshl_add_u64 v[72:73], s[10:11], 0, v[2:3]
	v_lshlrev_b32_e32 v2, 14, v13
	v_and_b32_e32 v2, 0xffff8000, v2
	v_lshl_add_u32 v2, v14, 11, v2
	v_and_b32_e32 v3, 1, v13
	v_lshl_or_b32 v2, v3, 6, v2
	v_lshl_add_u32 v2, v15, 1, v2
	v_mov_b32_e32 v3, v1
	s_add_u32 s8, s36, s8
	s_waitcnt vmcnt(6)
	v_lshl_add_u64 v[74:75], s[10:11], 0, v[2:3]
	s_addc_u32 s9, s37, 0
	v_readlane_b32 s10, v254, 24
	s_add_u32 s36, s10, s8
	v_readlane_b32 s8, v254, 26
	v_mov_b32_e32 v2, 0
	s_addc_u32 s37, s8, s9
	s_mov_b32 s38, -2
	s_mov_b64 s[8:9], 0
	v_add_u32_e32 v79, 0, v18
	v_mov_b32_e32 v3, v2
	v_mov_b32_e32 v4, v2
	v_mov_b32_e32 v5, v2
	v_mov_b32_e32 v6, v2
	v_mov_b32_e32 v7, v2
	v_mov_b32_e32 v8, v2
	v_mov_b32_e32 v9, v2
	v_mov_b32_e32 v18, v2
	v_mov_b32_e32 v19, v2
	v_mov_b32_e32 v20, v2
	v_mov_b32_e32 v21, v2
	v_mov_b32_e32 v22, v2
	v_mov_b32_e32 v23, v2
	v_mov_b32_e32 v24, v2
	v_mov_b32_e32 v25, v2
	v_mov_b32_e32 v34, v2
	v_mov_b32_e32 v35, v2
	v_mov_b32_e32 v36, v2
	v_mov_b32_e32 v37, v2
	v_mov_b32_e32 v38, v2
	v_mov_b32_e32 v39, v2
	v_mov_b32_e32 v40, v2
	v_mov_b32_e32 v41, v2
	v_mov_b32_e32 v50, v2
	v_mov_b32_e32 v51, v2
	v_mov_b32_e32 v52, v2
	v_mov_b32_e32 v53, v2
	v_mov_b32_e32 v54, v2
	v_mov_b32_e32 v55, v2
	v_mov_b32_e32 v56, v2
	v_mov_b32_e32 v57, v2
	v_mov_b32_e32 v10, v2
	v_mov_b32_e32 v11, v2
	v_mov_b32_e32 v12, v2
	v_mov_b32_e32 v13, v2
	v_mov_b32_e32 v14, v2
	v_mov_b32_e32 v15, v2
	v_mov_b32_e32 v16, v2
	v_mov_b32_e32 v17, v2
	v_mov_b32_e32 v26, v2
	v_mov_b32_e32 v27, v2
	v_mov_b32_e32 v28, v2
	v_mov_b32_e32 v29, v2
	v_mov_b32_e32 v30, v2
	v_mov_b32_e32 v31, v2
	v_mov_b32_e32 v32, v2
	v_mov_b32_e32 v33, v2
	v_mov_b32_e32 v42, v2
	v_mov_b32_e32 v43, v2
	v_mov_b32_e32 v44, v2
	v_mov_b32_e32 v45, v2
	v_mov_b32_e32 v46, v2
	v_mov_b32_e32 v47, v2
	v_mov_b32_e32 v48, v2
	v_mov_b32_e32 v49, v2
	v_mov_b32_e32 v58, v2
	v_mov_b32_e32 v59, v2
	v_mov_b32_e32 v60, v2
	v_mov_b32_e32 v61, v2
	v_mov_b32_e32 v62, v2
	v_mov_b32_e32 v63, v2
	v_mov_b32_e32 v64, v2
	v_mov_b32_e32 v65, v2
	v_mov_b32_e32 v82, v2
	v_mov_b32_e32 v83, v2
	v_mov_b32_e32 v84, v2
	v_mov_b32_e32 v85, v2
	v_mov_b32_e32 v86, v2
	v_mov_b32_e32 v87, v2
	v_mov_b32_e32 v88, v2
	v_mov_b32_e32 v89, v2
	v_mov_b32_e32 v98, v2
	v_mov_b32_e32 v99, v2
	v_mov_b32_e32 v100, v2
	v_mov_b32_e32 v101, v2
	v_mov_b32_e32 v102, v2
	v_mov_b32_e32 v103, v2
	v_mov_b32_e32 v104, v2
	v_mov_b32_e32 v105, v2
	v_mov_b32_e32 v114, v2
	v_mov_b32_e32 v115, v2
	v_mov_b32_e32 v116, v2
	v_mov_b32_e32 v117, v2
	v_mov_b32_e32 v118, v2
	v_mov_b32_e32 v119, v2
	v_mov_b32_e32 v120, v2
	v_mov_b32_e32 v121, v2
	v_mov_b32_e32 v130, v2
	v_mov_b32_e32 v131, v2
	v_mov_b32_e32 v132, v2
	v_mov_b32_e32 v133, v2
	v_mov_b32_e32 v134, v2
	v_mov_b32_e32 v135, v2
	v_mov_b32_e32 v136, v2
	v_mov_b32_e32 v137, v2
	v_mov_b32_e32 v90, v2
	v_mov_b32_e32 v91, v2
	v_mov_b32_e32 v92, v2
	v_mov_b32_e32 v93, v2
	v_mov_b32_e32 v94, v2
	v_mov_b32_e32 v95, v2
	v_mov_b32_e32 v96, v2
	v_mov_b32_e32 v97, v2
	v_mov_b32_e32 v106, v2
	v_mov_b32_e32 v107, v2
	v_mov_b32_e32 v108, v2
	v_mov_b32_e32 v109, v2
	v_mov_b32_e32 v110, v2
	v_mov_b32_e32 v111, v2
	v_mov_b32_e32 v112, v2
	v_mov_b32_e32 v113, v2
	v_mov_b32_e32 v122, v2
	v_mov_b32_e32 v123, v2
	v_mov_b32_e32 v124, v2
	v_mov_b32_e32 v125, v2
	v_mov_b32_e32 v126, v2
	v_mov_b32_e32 v127, v2
	v_mov_b32_e32 v128, v2
	v_mov_b32_e32 v129, v2
	v_mov_b32_e32 v138, v2
	v_mov_b32_e32 v139, v2
	v_mov_b32_e32 v140, v2
	v_mov_b32_e32 v141, v2
	v_mov_b32_e32 v142, v2
	v_mov_b32_e32 v143, v2
	v_mov_b32_e32 v144, v2
	v_mov_b32_e32 v145, v2
	s_barrier
.LBB0_534:
	s_add_u32 s10, s34, s8
	s_addc_u32 s11, s35, s9
	s_add_u32 s10, s10, 0x7000100
	s_addc_u32 s11, s11, 0
	s_add_u32 s39, s36, s8
	s_addc_u32 s42, s37, s9
	s_add_i32 s43, 0, 0x10000
	s_cmpk_eq_i32 s8, 0x700
	s_cselect_b32 s13, s5, s11
	s_cselect_b32 s12, s4, s10
	v_add_u32_e32 v80, s43, v78
	s_cselect_b32 s11, s7, s42
	s_cselect_b32 s10, s6, s39
	s_add_i32 s39, 0, 0x14000
	ds_read_b128 v[146:149], v80
	ds_read_b128 v[150:153], v80 offset:1024
	ds_read_b128 v[154:157], v80 offset:2048
	ds_read_b128 v[158:161], v80 offset:3072
	v_add_u32_e32 v80, s39, v78
	ds_read_b128 v[162:165], v80
	ds_read_b128 v[166:169], v80 offset:1024
	ds_read_b128 v[170:173], v80 offset:2048
	ds_read_b128 v[174:177], v80 offset:3072
	v_lshl_add_u64 v[80:81], v[72:73], 0, s[8:9]
	s_add_i32 m0, s22, 0xc000
	ds_read_b128 v[178:181], v79
	ds_read_b128 v[182:185], v79 offset:1024
	ds_read_b128 v[186:189], v79 offset:2048
	ds_read_b128 v[190:193], v79 offset:3072
	ds_read_b128 v[194:197], v79 offset:4096
	ds_read_b128 v[198:201], v79 offset:5120
	ds_read_b128 v[216:219], v79 offset:6144
	ds_read_b128 v[220:223], v79 offset:7168
	global_load_lds_dwordx4 v[80:81], off
	v_lshl_add_u64 v[80:81], v[74:75], 0, s[8:9]
	s_add_i32 m0, s22, 0xe000
	s_nop 0
	global_load_lds_dwordx4 v[80:81], off
	s_waitcnt vmcnt(8)
	s_waitcnt lgkmcnt(0)
	s_barrier
	s_setprio 1
	s_waitcnt lgkmcnt(0)
	v_mfma_f32_16x16x32_bf16 v[142:145], v[146:149], v[178:181], v[142:145]
	v_mfma_f32_16x16x32_bf16 v[138:141], v[154:157], v[178:181], v[138:141]
	v_mfma_f32_16x16x32_bf16 v[126:129], v[146:149], v[186:189], v[126:129]
	v_mfma_f32_16x16x32_bf16 v[122:125], v[154:157], v[186:189], v[122:125]
	v_mfma_f32_16x16x32_bf16 v[110:113], v[146:149], v[194:197], v[110:113]
	v_mfma_f32_16x16x32_bf16 v[106:109], v[154:157], v[194:197], v[106:109]
	v_mfma_f32_16x16x32_bf16 v[94:97], v[146:149], v[216:219], v[94:97]
	v_mfma_f32_16x16x32_bf16 v[90:93], v[154:157], v[216:219], v[90:93]
	v_mfma_f32_16x16x32_bf16 v[142:145], v[150:153], v[182:185], v[142:145]
	v_mfma_f32_16x16x32_bf16 v[138:141], v[158:161], v[182:185], v[138:141]
	v_mfma_f32_16x16x32_bf16 v[126:129], v[150:153], v[190:193], v[126:129]
	v_mfma_f32_16x16x32_bf16 v[122:125], v[158:161], v[190:193], v[122:125]
	v_mfma_f32_16x16x32_bf16 v[110:113], v[150:153], v[198:201], v[110:113]
	v_mfma_f32_16x16x32_bf16 v[106:109], v[158:161], v[198:201], v[106:109]
	v_mfma_f32_16x16x32_bf16 v[94:97], v[150:153], v[220:223], v[94:97]
	v_mfma_f32_16x16x32_bf16 v[90:93], v[158:161], v[220:223], v[90:93]
	s_setprio 0
	s_setprio 1
	v_mfma_f32_16x16x32_bf16 v[134:137], v[162:165], v[178:181], v[134:137]
	v_mfma_f32_16x16x32_bf16 v[130:133], v[170:173], v[178:181], v[130:133]
	v_mfma_f32_16x16x32_bf16 v[118:121], v[162:165], v[186:189], v[118:121]
	v_mfma_f32_16x16x32_bf16 v[114:117], v[170:173], v[186:189], v[114:117]
	v_mfma_f32_16x16x32_bf16 v[102:105], v[162:165], v[194:197], v[102:105]
	v_mfma_f32_16x16x32_bf16 v[98:101], v[170:173], v[194:197], v[98:101]
	v_mfma_f32_16x16x32_bf16 v[86:89], v[162:165], v[216:219], v[86:89]
	v_mfma_f32_16x16x32_bf16 v[80:83], v[170:173], v[216:219], v[82:85]
	v_mfma_f32_16x16x32_bf16 v[134:137], v[166:169], v[182:185], v[134:137]
	v_mfma_f32_16x16x32_bf16 v[130:133], v[174:177], v[182:185], v[130:133]
	v_mfma_f32_16x16x32_bf16 v[118:121], v[166:169], v[190:193], v[118:121]
	v_mfma_f32_16x16x32_bf16 v[114:117], v[174:177], v[190:193], v[114:117]
	v_mfma_f32_16x16x32_bf16 v[102:105], v[166:169], v[198:201], v[102:105]
	v_mfma_f32_16x16x32_bf16 v[98:101], v[174:177], v[198:201], v[98:101]
	v_mfma_f32_16x16x32_bf16 v[86:89], v[166:169], v[220:223], v[86:89]
	v_mfma_f32_16x16x32_bf16 v[80:83], v[174:177], v[220:223], v[80:83]
	s_setprio 0
	s_barrier
	s_add_i32 s42, s43, s21
	v_lshl_add_u64 v[208:209], s[10:11], 0, v[0:1]
	s_mov_b32 m0, s42
	ds_read_b128 v[178:181], v79 offset:16384
	ds_read_b128 v[182:185], v79 offset:17408
	ds_read_b128 v[186:189], v79 offset:18432
	ds_read_b128 v[190:193], v79 offset:19456
	ds_read_b128 v[194:197], v79 offset:20480
	ds_read_b128 v[198:201], v79 offset:21504
	ds_read_b128 v[216:219], v79 offset:22528
	ds_read_b128 v[220:223], v79 offset:23552
	global_load_lds_dwordx4 v[208:209], off
	s_add_i32 m0, s42, 0x2000
	s_add_u32 s42, s10, 0x40000
	v_lshl_add_u64 v[224:225], s[10:11], 0, v[70:71]
	s_addc_u32 s43, s11, 0
	s_add_i32 s39, s39, s21
	global_load_lds_dwordx4 v[224:225], off
	v_lshl_add_u64 v[84:85], s[42:43], 0, v[0:1]
	s_mov_b32 m0, s39
	v_lshl_add_u64 v[226:227], s[12:13], 0, v[66:67]
	global_load_lds_dwordx4 v[84:85], off
	v_lshl_add_u64 v[84:85], s[42:43], 0, v[70:71]
	s_add_i32 m0, s39, 0x2000
	v_lshl_add_u64 v[228:229], s[12:13], 0, v[68:69]
	global_load_lds_dwordx4 v[84:85], off
	s_mov_b32 m0, s22
	s_nop 0
	global_load_lds_dwordx4 v[226:227], off
	s_mov_b32 m0, s23
	s_nop 0
	global_load_lds_dwordx4 v[228:229], off
	s_waitcnt vmcnt(8)
	s_waitcnt lgkmcnt(0)
	s_barrier
	s_setprio 1
	s_waitcnt lgkmcnt(0)
	v_mfma_f32_16x16x32_bf16 v[62:65], v[146:149], v[178:181], v[62:65]
	v_mfma_f32_16x16x32_bf16 v[58:61], v[154:157], v[178:181], v[58:61]
	v_mfma_f32_16x16x32_bf16 v[46:49], v[146:149], v[186:189], v[46:49]
	v_mfma_f32_16x16x32_bf16 v[42:45], v[154:157], v[186:189], v[42:45]
	v_mfma_f32_16x16x32_bf16 v[30:33], v[146:149], v[194:197], v[30:33]
	v_mfma_f32_16x16x32_bf16 v[26:29], v[154:157], v[194:197], v[26:29]
	v_mfma_f32_16x16x32_bf16 v[14:17], v[146:149], v[216:219], v[14:17]
	v_mfma_f32_16x16x32_bf16 v[10:13], v[154:157], v[216:219], v[10:13]
	v_mfma_f32_16x16x32_bf16 v[62:65], v[150:153], v[182:185], v[62:65]
	v_mfma_f32_16x16x32_bf16 v[58:61], v[158:161], v[182:185], v[58:61]
	v_mfma_f32_16x16x32_bf16 v[46:49], v[150:153], v[190:193], v[46:49]
	v_mfma_f32_16x16x32_bf16 v[42:45], v[158:161], v[190:193], v[42:45]
	v_mfma_f32_16x16x32_bf16 v[30:33], v[150:153], v[198:201], v[30:33]
	v_mfma_f32_16x16x32_bf16 v[26:29], v[158:161], v[198:201], v[26:29]
	v_mfma_f32_16x16x32_bf16 v[14:17], v[150:153], v[220:223], v[14:17]
	v_mfma_f32_16x16x32_bf16 v[10:13], v[158:161], v[220:223], v[10:13]
	s_setprio 0
	s_setprio 1
	v_mfma_f32_16x16x32_bf16 v[54:57], v[162:165], v[178:181], v[54:57]
	v_mfma_f32_16x16x32_bf16 v[50:53], v[170:173], v[178:181], v[50:53]
	v_mfma_f32_16x16x32_bf16 v[38:41], v[162:165], v[186:189], v[38:41]
	v_mfma_f32_16x16x32_bf16 v[34:37], v[170:173], v[186:189], v[34:37]
	v_mfma_f32_16x16x32_bf16 v[22:25], v[162:165], v[194:197], v[22:25]
	v_mfma_f32_16x16x32_bf16 v[18:21], v[170:173], v[194:197], v[18:21]
	v_mfma_f32_16x16x32_bf16 v[6:9], v[162:165], v[216:219], v[6:9]
	v_mfma_f32_16x16x32_bf16 v[2:5], v[170:173], v[216:219], v[2:5]
	v_mfma_f32_16x16x32_bf16 v[54:57], v[166:169], v[182:185], v[54:57]
	v_mfma_f32_16x16x32_bf16 v[50:53], v[174:177], v[182:185], v[50:53]
	v_mfma_f32_16x16x32_bf16 v[38:41], v[166:169], v[190:193], v[38:41]
	v_mfma_f32_16x16x32_bf16 v[34:37], v[174:177], v[190:193], v[34:37]
	v_mfma_f32_16x16x32_bf16 v[22:25], v[166:169], v[198:201], v[22:25]
	v_mfma_f32_16x16x32_bf16 v[18:21], v[174:177], v[198:201], v[18:21]
	v_mfma_f32_16x16x32_bf16 v[6:9], v[166:169], v[220:223], v[6:9]
	v_mfma_f32_16x16x32_bf16 v[2:5], v[174:177], v[220:223], v[2:5]
	s_setprio 0
	s_barrier
	s_add_i32 s39, 0, 0x18000
	v_add_u32_e32 v84, s39, v78
	s_add_i32 s42, 0, 0x1c000
	ds_read_b128 v[146:149], v84
	ds_read_b128 v[150:153], v84 offset:1024
	ds_read_b128 v[154:157], v84 offset:2048
	ds_read_b128 v[158:161], v84 offset:3072
	v_add_u32_e32 v84, s42, v78
	ds_read_b128 v[162:165], v84
	ds_read_b128 v[166:169], v84 offset:1024
	ds_read_b128 v[170:173], v84 offset:2048
	ds_read_b128 v[174:177], v84 offset:3072
	s_add_u32 s12, s12, 0x40000
	s_addc_u32 s13, s13, 0
	s_mov_b32 m0, s25
	v_lshl_add_u64 v[84:85], s[12:13], 0, v[66:67]
	ds_read_b128 v[178:181], v79 offset:32768
	ds_read_b128 v[182:185], v79 offset:33792
	ds_read_b128 v[186:189], v79 offset:34816
	ds_read_b128 v[190:193], v79 offset:35840
	ds_read_b128 v[194:197], v79 offset:36864
	ds_read_b128 v[198:201], v79 offset:37888
	ds_read_b128 v[216:219], v79 offset:38912
	ds_read_b128 v[220:223], v79 offset:39936
	global_load_lds_dwordx4 v[84:85], off
	v_lshl_add_u64 v[84:85], s[12:13], 0, v[68:69]
	s_mov_b32 m0, s27
	s_nop 0
	global_load_lds_dwordx4 v[84:85], off
	s_waitcnt vmcnt(8)
	s_waitcnt lgkmcnt(0)
	s_barrier
	s_setprio 1
	s_waitcnt lgkmcnt(0)
	v_mfma_f32_16x16x32_bf16 v[142:145], v[146:149], v[178:181], v[142:145]
	v_mfma_f32_16x16x32_bf16 v[138:141], v[154:157], v[178:181], v[138:141]
	v_mfma_f32_16x16x32_bf16 v[126:129], v[146:149], v[186:189], v[126:129]
	v_mfma_f32_16x16x32_bf16 v[122:125], v[154:157], v[186:189], v[122:125]
	v_mfma_f32_16x16x32_bf16 v[110:113], v[146:149], v[194:197], v[110:113]
	v_mfma_f32_16x16x32_bf16 v[106:109], v[154:157], v[194:197], v[106:109]
	v_mfma_f32_16x16x32_bf16 v[94:97], v[146:149], v[216:219], v[94:97]
	v_mfma_f32_16x16x32_bf16 v[90:93], v[154:157], v[216:219], v[90:93]
	v_mfma_f32_16x16x32_bf16 v[142:145], v[150:153], v[182:185], v[142:145]
	v_mfma_f32_16x16x32_bf16 v[138:141], v[158:161], v[182:185], v[138:141]
	v_mfma_f32_16x16x32_bf16 v[126:129], v[150:153], v[190:193], v[126:129]
	v_mfma_f32_16x16x32_bf16 v[122:125], v[158:161], v[190:193], v[122:125]
	v_mfma_f32_16x16x32_bf16 v[110:113], v[150:153], v[198:201], v[110:113]
	v_mfma_f32_16x16x32_bf16 v[106:109], v[158:161], v[198:201], v[106:109]
	v_mfma_f32_16x16x32_bf16 v[94:97], v[150:153], v[220:223], v[94:97]
	v_mfma_f32_16x16x32_bf16 v[90:93], v[158:161], v[220:223], v[90:93]
	s_setprio 0
	s_setprio 1
	v_mfma_f32_16x16x32_bf16 v[134:137], v[162:165], v[178:181], v[134:137]
	v_mfma_f32_16x16x32_bf16 v[130:133], v[170:173], v[178:181], v[130:133]
	v_mfma_f32_16x16x32_bf16 v[118:121], v[162:165], v[186:189], v[118:121]
	v_mfma_f32_16x16x32_bf16 v[114:117], v[170:173], v[186:189], v[114:117]
	v_mfma_f32_16x16x32_bf16 v[102:105], v[162:165], v[194:197], v[102:105]
	v_mfma_f32_16x16x32_bf16 v[98:101], v[170:173], v[194:197], v[98:101]
	v_mfma_f32_16x16x32_bf16 v[84:87], v[162:165], v[216:219], v[86:89]
	v_mfma_f32_16x16x32_bf16 v[80:83], v[170:173], v[216:219], v[80:83]
	v_mfma_f32_16x16x32_bf16 v[134:137], v[166:169], v[182:185], v[134:137]
	v_mfma_f32_16x16x32_bf16 v[130:133], v[174:177], v[182:185], v[130:133]
	v_mfma_f32_16x16x32_bf16 v[118:121], v[166:169], v[190:193], v[118:121]
	v_mfma_f32_16x16x32_bf16 v[114:117], v[174:177], v[190:193], v[114:117]
	v_mfma_f32_16x16x32_bf16 v[102:105], v[166:169], v[198:201], v[102:105]
	v_mfma_f32_16x16x32_bf16 v[98:101], v[174:177], v[198:201], v[98:101]
	v_mfma_f32_16x16x32_bf16 v[86:89], v[166:169], v[220:223], v[84:87]
	v_mfma_f32_16x16x32_bf16 v[82:85], v[174:177], v[220:223], v[80:83]
	s_setprio 0
	s_barrier
	s_add_i32 s12, s39, s21
	v_lshl_add_u64 v[80:81], v[208:209], 0, s[96:97]
	s_mov_b32 m0, s12
	ds_read_b128 v[178:181], v79 offset:49152
	ds_read_b128 v[182:185], v79 offset:50176
	ds_read_b128 v[186:189], v79 offset:51200
	ds_read_b128 v[190:193], v79 offset:52224
	ds_read_b128 v[194:197], v79 offset:53248
	ds_read_b128 v[198:201], v79 offset:54272
	ds_read_b128 v[216:219], v79 offset:55296
	ds_read_b128 v[220:223], v79 offset:56320
	global_load_lds_dwordx4 v[80:81], off
	s_add_i32 m0, s12, 0x2000
	s_add_u32 s10, s10, 0x40080
	v_lshl_add_u64 v[80:81], v[224:225], 0, s[96:97]
	s_addc_u32 s11, s11, 0
	s_add_i32 s12, s42, s21
	global_load_lds_dwordx4 v[80:81], off
	v_lshl_add_u64 v[80:81], s[10:11], 0, v[0:1]
	s_mov_b32 m0, s12
	s_nop 0
	global_load_lds_dwordx4 v[80:81], off
	v_lshl_add_u64 v[80:81], s[10:11], 0, v[70:71]
	s_add_i32 m0, s12, 0x2000
	s_nop 0
	global_load_lds_dwordx4 v[80:81], off
	v_lshl_add_u64 v[80:81], v[226:227], 0, s[96:97]
	s_mov_b32 m0, s30
	s_nop 0
	global_load_lds_dwordx4 v[80:81], off
	v_lshl_add_u64 v[80:81], v[228:229], 0, s[96:97]
	s_mov_b32 m0, s33
	s_nop 0
	global_load_lds_dwordx4 v[80:81], off
	s_waitcnt vmcnt(8)
	s_waitcnt lgkmcnt(0)
	s_barrier
	s_setprio 1
	s_waitcnt lgkmcnt(0)
	v_mfma_f32_16x16x32_bf16 v[62:65], v[146:149], v[178:181], v[62:65]
	v_mfma_f32_16x16x32_bf16 v[58:61], v[154:157], v[178:181], v[58:61]
	v_mfma_f32_16x16x32_bf16 v[46:49], v[146:149], v[186:189], v[46:49]
	v_mfma_f32_16x16x32_bf16 v[42:45], v[154:157], v[186:189], v[42:45]
	v_mfma_f32_16x16x32_bf16 v[30:33], v[146:149], v[194:197], v[30:33]
	v_mfma_f32_16x16x32_bf16 v[26:29], v[154:157], v[194:197], v[26:29]
	v_mfma_f32_16x16x32_bf16 v[14:17], v[146:149], v[216:219], v[14:17]
	v_mfma_f32_16x16x32_bf16 v[10:13], v[154:157], v[216:219], v[10:13]
	v_mfma_f32_16x16x32_bf16 v[62:65], v[150:153], v[182:185], v[62:65]
	v_mfma_f32_16x16x32_bf16 v[58:61], v[158:161], v[182:185], v[58:61]
	v_mfma_f32_16x16x32_bf16 v[46:49], v[150:153], v[190:193], v[46:49]
	v_mfma_f32_16x16x32_bf16 v[42:45], v[158:161], v[190:193], v[42:45]
	v_mfma_f32_16x16x32_bf16 v[30:33], v[150:153], v[198:201], v[30:33]
	v_mfma_f32_16x16x32_bf16 v[26:29], v[158:161], v[198:201], v[26:29]
	v_mfma_f32_16x16x32_bf16 v[14:17], v[150:153], v[220:223], v[14:17]
	v_mfma_f32_16x16x32_bf16 v[10:13], v[158:161], v[220:223], v[10:13]
	s_setprio 0
	s_setprio 1
	v_mfma_f32_16x16x32_bf16 v[54:57], v[162:165], v[178:181], v[54:57]
	v_mfma_f32_16x16x32_bf16 v[50:53], v[170:173], v[178:181], v[50:53]
	v_mfma_f32_16x16x32_bf16 v[38:41], v[162:165], v[186:189], v[38:41]
	v_mfma_f32_16x16x32_bf16 v[34:37], v[170:173], v[186:189], v[34:37]
	v_mfma_f32_16x16x32_bf16 v[22:25], v[162:165], v[194:197], v[22:25]
	v_mfma_f32_16x16x32_bf16 v[18:21], v[170:173], v[194:197], v[18:21]
	v_mfma_f32_16x16x32_bf16 v[6:9], v[162:165], v[216:219], v[6:9]
	v_mfma_f32_16x16x32_bf16 v[2:5], v[170:173], v[216:219], v[2:5]
	v_mfma_f32_16x16x32_bf16 v[54:57], v[166:169], v[182:185], v[54:57]
	v_mfma_f32_16x16x32_bf16 v[50:53], v[174:177], v[182:185], v[50:53]
	v_mfma_f32_16x16x32_bf16 v[38:41], v[166:169], v[190:193], v[38:41]
	v_mfma_f32_16x16x32_bf16 v[34:37], v[174:177], v[190:193], v[34:37]
	v_mfma_f32_16x16x32_bf16 v[22:25], v[166:169], v[198:201], v[22:25]
	v_mfma_f32_16x16x32_bf16 v[18:21], v[174:177], v[198:201], v[18:21]
	v_mfma_f32_16x16x32_bf16 v[6:9], v[166:169], v[220:223], v[6:9]
	v_mfma_f32_16x16x32_bf16 v[2:5], v[174:177], v[220:223], v[2:5]
	s_setprio 0
	s_barrier
	s_add_i32 s38, s38, 2
	s_add_u32 s8, s8, 0x100
	s_addc_u32 s9, s9, 0
	s_cmp_gt_u32 s38, 13
	s_cbranch_scc0 .LBB0_534
	s_cmpk_lt_u32 s3, 0x100
	s_cbranch_scc0 .LBB0_537
	s_barrier

.LBB0_647:
	s_andn2_b64 vcc, exec, s[4:5]
	s_cbranch_vccnz .LBB0_670
	v_readlane_b32 s4, v254, 37
	s_cmp_lg_u32 s4, 3
	v_readlane_b32 s5, v254, 38
	v_readlane_b32 s6, v254, 39
	v_readlane_b32 s7, v254, 40
	s_cbranch_scc1 .LBB0_670
	v_lshl_add_u32 v2, s26, 9, v63
	s_mov_b32 s2, 0x80000
	s_lshl_b32 s4, s27, 9
	v_cmp_gt_i32_e32 vcc, s2, v2
	v_and_b32_e32 v4, 63, v63
	v_and_b32_e32 v10, 0x1ff, v63
	v_ashrrev_i32_e32 v3, 31, v2
	s_and_saveexec_b64 s[6:7], vcc
	v_readlane_b32 s8, v253, 33
	v_readlane_b32 s16, v253, 41
	v_readlane_b32 s12, v253, 37
	v_readlane_b32 s13, v253, 38
	v_readlane_b32 s14, v253, 39
	v_readlane_b32 s15, v253, 40
	s_mov_b32 s16, 0x7ffff
	v_readlane_b32 s9, v253, 34
	v_readlane_b32 s10, v253, 35
	v_readlane_b32 s11, v253, 36
	v_readlane_b32 s17, v253, 42
	v_readlane_b32 s18, v253, 43
	v_readlane_b32 s19, v253, 44
	v_readlane_b32 s20, v253, 45
	v_readlane_b32 s21, v253, 46
	v_readlane_b32 s22, v253, 47
	v_readlane_b32 s23, v253, 48
	s_cbranch_execz .LBB0_652
	v_readlane_b32 s2, v252, 58
	v_readlane_b32 s8, v254, 43
	v_readlane_b32 s9, v254, 44
	s_add_u32 s2, s2, s8
	v_readlane_b32 s3, v252, 59
	s_addc_u32 s3, s3, s9
	s_ashr_i32 s5, s4, 31
	v_mov_b32_e32 v168, v2
	s_mul_i32 s10, s4, 3
.Lcc1_top:
	v_add_u32_e32 v169, s10, v168
	v_cmp_gt_i32_e32 vcc, 0x80000, v169
	s_cmp_eq_u64 vcc, exec
	s_cbranch_scc0 .Lcc1_tail
	v_mov_b32_e32 v170, v168
	v_add_u32_e32 v171, s4, v170
	v_add_u32_e32 v172, s4, v171
	v_add_u32_e32 v173, s4, v172
	v_and_b32_e32 v190, 0x7fc0, v170
	v_lshrrev_b32_e32 v194, 9, v170
	v_and_b32_e32 v174, 0x4003f, v170
	v_lshl_or_b32 v174, v190, 3, v174
	v_and_b32_e32 v190, 0x1c0, v194
	v_or_b32_e32 v174, v174, v190
	v_lshlrev_b32_e32 v174, 2, v174
	v_and_b32_e32 v190, 0x1ff, v170
	v_and_b32_e32 v178, 0x40000, v170
	v_lshl_or_b32 v178, v190, 9, v178
	v_and_b32_e32 v194, 0x1ff, v194
	v_or_b32_e32 v178, v178, v194
	v_lshlrev_b32_e32 v178, 2, v178
	v_and_b32_e32 v191, 0x7fc0, v171
	v_lshrrev_b32_e32 v195, 9, v171
	v_and_b32_e32 v175, 0x4003f, v171
	v_lshl_or_b32 v175, v191, 3, v175
	v_and_b32_e32 v191, 0x1c0, v195
	v_or_b32_e32 v175, v175, v191
	v_lshlrev_b32_e32 v175, 2, v175
	v_and_b32_e32 v191, 0x1ff, v171
	v_and_b32_e32 v179, 0x40000, v171
	v_lshl_or_b32 v179, v191, 9, v179
	v_and_b32_e32 v195, 0x1ff, v195
	v_or_b32_e32 v179, v179, v195
	v_lshlrev_b32_e32 v179, 2, v179
	v_and_b32_e32 v192, 0x7fc0, v172
	v_lshrrev_b32_e32 v196, 9, v172
	v_and_b32_e32 v176, 0x4003f, v172
	v_lshl_or_b32 v176, v192, 3, v176
	v_and_b32_e32 v192, 0x1c0, v196
	v_or_b32_e32 v176, v176, v192
	v_lshlrev_b32_e32 v176, 2, v176
	v_and_b32_e32 v192, 0x1ff, v172
	v_and_b32_e32 v180, 0x40000, v172
	v_lshl_or_b32 v180, v192, 9, v180
	v_and_b32_e32 v196, 0x1ff, v196
	v_or_b32_e32 v180, v180, v196
	v_lshlrev_b32_e32 v180, 2, v180
	v_and_b32_e32 v193, 0x7fc0, v173
	v_lshrrev_b32_e32 v197, 9, v173
	v_and_b32_e32 v177, 0x4003f, v173
	v_lshl_or_b32 v177, v193, 3, v177
	v_and_b32_e32 v193, 0x1c0, v197
	v_or_b32_e32 v177, v177, v193
	v_lshlrev_b32_e32 v177, 2, v177
	v_and_b32_e32 v193, 0x1ff, v173
	v_and_b32_e32 v181, 0x40000, v173
	v_lshl_or_b32 v181, v193, 9, v181
	v_and_b32_e32 v197, 0x1ff, v197
	v_or_b32_e32 v181, v181, v197
	v_lshlrev_b32_e32 v181, 2, v181
	global_load_dword v182, v174, s[12:13]
	global_load_dword v186, v178, s[14:15]
	global_load_dword v183, v175, s[12:13]
	global_load_dword v187, v179, s[14:15]
	global_load_dword v184, v176, s[12:13]
	global_load_dword v188, v180, s[14:15]
	global_load_dword v185, v177, s[12:13]
	global_load_dword v189, v181, s[14:15]
	v_lshlrev_b32_e32 v190, 1, v170
	v_add_u32_e32 v194, 0x100000, v190
	v_lshlrev_b32_e32 v191, 1, v171
	v_add_u32_e32 v195, 0x100000, v191
	v_lshlrev_b32_e32 v192, 1, v172
	v_add_u32_e32 v196, 0x100000, v192
	v_lshlrev_b32_e32 v193, 1, v173
	v_add_u32_e32 v197, 0x100000, v193
	s_waitcnt vmcnt(0)
	v_cvt_pk_bf16_f32 v182, v182, v182
	v_cvt_pk_bf16_f32 v186, v186, v186
	v_cvt_pk_bf16_f32 v183, v183, v183
	v_cvt_pk_bf16_f32 v187, v187, v187
	v_cvt_pk_bf16_f32 v184, v184, v184
	v_cvt_pk_bf16_f32 v188, v188, v188
	v_cvt_pk_bf16_f32 v185, v185, v185
	v_cvt_pk_bf16_f32 v189, v189, v189
	global_store_short v190, v182, s[2:3]
	global_store_short v194, v186, s[2:3]
	global_store_short v191, v183, s[2:3]
	global_store_short v195, v187, s[2:3]
	global_store_short v192, v184, s[2:3]
	global_store_short v196, v188, s[2:3]
	global_store_short v193, v185, s[2:3]
	global_store_short v197, v189, s[2:3]
	v_lshl_add_u32 v168, s4, 2, v168
	s_branch .Lcc1_top
.Lcc1_tail:
	v_cmp_gt_i32_e32 vcc, 0x80000, v168
	s_and_b64 exec, exec, vcc
	s_cbranch_execz .LBB0_652
	v_ashrrev_i32_e32 v169, 31, v168
	v_lshl_add_u64 v[6:7], v[168:169], 1, s[2:3]
	s_lshl_b64 s[8:9], s[4:5], 1
	s_mov_b64 s[10:11], 0
	v_lshlrev_b32_e32 v8, 2, v4
	v_mov_b32_e32 v5, v168

.LBB0_652:
	s_or_b64 exec, exec, s[6:7]
	s_mov_b32 s2, 0x20000
	v_cmp_gt_i32_e32 vcc, s2, v2
	s_and_saveexec_b64 s[6:7], vcc
	v_readlane_b32 s8, v253, 33
	v_readlane_b32 s12, v253, 37
	v_readlane_b32 s16, v253, 41
	v_readlane_b32 s17, v253, 42
	v_readlane_b32 s18, v253, 43
	v_readlane_b32 s19, v253, 44
	s_mov_b32 s12, 0x1ffff
	v_readlane_b32 s9, v253, 34
	v_readlane_b32 s10, v253, 35
	v_readlane_b32 s11, v253, 36
	v_readlane_b32 s13, v253, 38
	v_readlane_b32 s14, v253, 39
	v_readlane_b32 s15, v253, 40
	v_readlane_b32 s20, v253, 45
	v_readlane_b32 s21, v253, 46
	v_readlane_b32 s22, v253, 47
	v_readlane_b32 s23, v253, 48
	s_cbranch_execz .LBB0_655
	v_readlane_b32 s2, v252, 60
	v_readlane_b32 s8, v254, 43
	v_readlane_b32 s9, v254, 44
	s_add_u32 s2, s2, s8
	v_readlane_b32 s3, v252, 61
	s_addc_u32 s3, s3, s9
	s_ashr_i32 s5, s4, 31
	v_mov_b32_e32 v168, v2
	s_mul_i32 s10, s4, 3
.Lcc2_top:
	v_add_u32_e32 v169, s10, v168
	v_cmp_gt_i32_e32 vcc, 0x20000, v169
	s_cmp_eq_u64 vcc, exec
	s_cbranch_scc0 .Lcc2_tail
	v_mov_b32_e32 v170, v168
	v_add_u32_e32 v171, s4, v170
	v_add_u32_e32 v172, s4, v171
	v_add_u32_e32 v173, s4, v172
	v_and_b32_e32 v190, 0x7fc0, v170
	v_lshrrev_b32_e32 v194, 9, v170
	v_and_b32_e32 v174, 0x1003f, v170
	v_lshl_or_b32 v174, v190, 1, v174
	v_and_b32_e32 v190, 0x40, v194
	v_or_b32_e32 v174, v174, v190
	v_lshlrev_b32_e32 v174, 2, v174
	v_and_b32_e32 v190, 0x1ff, v170
	v_and_b32_e32 v178, 0x10000, v170
	v_lshl_or_b32 v178, v190, 7, v178
	v_and_b32_e32 v194, 0x7f, v194
	v_or_b32_e32 v178, v178, v194
	v_lshlrev_b32_e32 v178, 2, v178
	v_and_b32_e32 v191, 0x7fc0, v171
	v_lshrrev_b32_e32 v195, 9, v171
	v_and_b32_e32 v175, 0x1003f, v171
	v_lshl_or_b32 v175, v191, 1, v175
	v_and_b32_e32 v191, 0x40, v195
	v_or_b32_e32 v175, v175, v191
	v_lshlrev_b32_e32 v175, 2, v175
	v_and_b32_e32 v191, 0x1ff, v171
	v_and_b32_e32 v179, 0x10000, v171
	v_lshl_or_b32 v179, v191, 7, v179
	v_and_b32_e32 v195, 0x7f, v195
	v_or_b32_e32 v179, v179, v195
	v_lshlrev_b32_e32 v179, 2, v179
	v_and_b32_e32 v192, 0x7fc0, v172
	v_lshrrev_b32_e32 v196, 9, v172
	v_and_b32_e32 v176, 0x1003f, v172
	v_lshl_or_b32 v176, v192, 1, v176
	v_and_b32_e32 v192, 0x40, v196
	v_or_b32_e32 v176, v176, v192
	v_lshlrev_b32_e32 v176, 2, v176
	v_and_b32_e32 v192, 0x1ff, v172
	v_and_b32_e32 v180, 0x10000, v172
	v_lshl_or_b32 v180, v192, 7, v180
	v_and_b32_e32 v196, 0x7f, v196
	v_or_b32_e32 v180, v180, v196
	v_lshlrev_b32_e32 v180, 2, v180
	v_and_b32_e32 v193, 0x7fc0, v173
	v_lshrrev_b32_e32 v197, 9, v173
	v_and_b32_e32 v177, 0x1003f, v173
	v_lshl_or_b32 v177, v193, 1, v177
	v_and_b32_e32 v193, 0x40, v197
	v_or_b32_e32 v177, v177, v193
	v_lshlrev_b32_e32 v177, 2, v177
	v_and_b32_e32 v193, 0x1ff, v173
	v_and_b32_e32 v181, 0x10000, v173
	v_lshl_or_b32 v181, v193, 7, v181
	v_and_b32_e32 v197, 0x7f, v197
	v_or_b32_e32 v181, v181, v197
	v_lshlrev_b32_e32 v181, 2, v181
	global_load_dword v182, v174, s[16:17]
	global_load_dword v186, v178, s[18:19]
	global_load_dword v183, v175, s[16:17]
	global_load_dword v187, v179, s[18:19]
	global_load_dword v184, v176, s[16:17]
	global_load_dword v188, v180, s[18:19]
	global_load_dword v185, v177, s[16:17]
	global_load_dword v189, v181, s[18:19]
	v_lshlrev_b32_e32 v190, 1, v170
	v_add_u32_e32 v194, 0x40000, v190
	v_lshlrev_b32_e32 v191, 1, v171
	v_add_u32_e32 v195, 0x40000, v191
	v_lshlrev_b32_e32 v192, 1, v172
	v_add_u32_e32 v196, 0x40000, v192
	v_lshlrev_b32_e32 v193, 1, v173
	v_add_u32_e32 v197, 0x40000, v193
	s_waitcnt vmcnt(0)
	v_cvt_pk_bf16_f32 v182, v182, v182
	v_cvt_pk_bf16_f32 v186, v186, v186
	v_cvt_pk_bf16_f32 v183, v183, v183
	v_cvt_pk_bf16_f32 v187, v187, v187
	v_cvt_pk_bf16_f32 v184, v184, v184
	v_cvt_pk_bf16_f32 v188, v188, v188
	v_cvt_pk_bf16_f32 v185, v185, v185
	v_cvt_pk_bf16_f32 v189, v189, v189
	global_store_short v190, v182, s[2:3]
	global_store_short v194, v186, s[2:3]
	global_store_short v191, v183, s[2:3]
	global_store_short v195, v187, s[2:3]
	global_store_short v192, v184, s[2:3]
	global_store_short v196, v188, s[2:3]
	global_store_short v193, v185, s[2:3]
	global_store_short v197, v189, s[2:3]
	v_lshl_add_u32 v168, s4, 2, v168
	s_branch .Lcc2_top
.Lcc2_tail:
	v_cmp_gt_i32_e32 vcc, 0x20000, v168
	s_and_b64 exec, exec, vcc
	s_cbranch_execz .LBB0_655
	v_mov_b32_e32 v2, v168
	v_ashrrev_i32_e32 v3, 31, v2
	v_lshl_add_u64 v[6:7], v[2:3], 1, s[2:3]
	s_lshl_b64 s[8:9], s[4:5], 1
	s_mov_b64 s[10:11], 0
	v_lshlrev_b32_e32 v4, 2, v4

.LBB0_686:
	s_or_b64 exec, exec, s[0:1]
	s_waitcnt lgkmcnt(0)
	s_barrier
	ds_read_b32 v0, v1 offset:38912
	s_mov_b64 s[0:1], -1
	s_waitcnt lgkmcnt(0)
	v_readfirstlane_b32 s12, v0
	s_cmpk_gt_i32 s12, 0x2ff
	s_cbranch_scc1 .LBB0_681
	s_cmpk_gt_i32 s12, 0x7f
	s_mov_b64 s[10:11], -1
	s_cbranch_scc1 .LBB0_800
	s_andn2_b64 vcc, exec, s[10:11]
	s_cbranch_vccz .LBB0_812

.LBB0_819:
	s_and_b64 s[8:9], s[8:9], exec
	s_cselect_b32 s3, 0, 32
	s_add_i32 s30, s12, s3
	s_add_u32 s40, s72, 0x7800000
	s_addc_u32 s41, s73, 0
	v_readlane_b32 s8, v254, 33
	v_readlane_b32 s3, v254, 56
	v_readlane_b32 s9, v254, 34
	s_add_u32 s42, s3, s8
	v_readlane_b32 s3, v254, 57
	s_addc_u32 s43, s3, s9
	v_readlane_b32 s8, v254, 35
	v_readlane_b32 s3, v254, 55
	v_readlane_b32 s9, v254, 36
	s_add_u32 s3, s3, s8
	v_readlane_b32 s8, v254, 48
	s_addc_u32 s12, s8, s9
	s_lshl_b32 s25, s2, 6
	s_lshl_b32 s29, s2, 13
	s_lshl_b32 s2, s26, 5
	s_and_b32 s26, s2, 0x60
	s_add_i32 m0, s13, 0x18000
	v_lshl_add_u64 v[8:9], v[8:9], 0, s[96:97]
	s_lshl_b32 s33, s26, 7
	s_waitcnt vmcnt(2)
	s_barrier
	global_load_lds_dwordx4 v[8:9], off
	v_lshl_add_u64 v[6:7], v[6:7], 0, s[96:97]
	s_add_i32 m0, s13, 0x1a000
	s_add_i32 s27, s13, 0x8000
	s_add_i32 s28, s13, 0xa000
	global_load_lds_dwordx4 v[6:7], off
	v_lshl_add_u64 v[2:3], v[2:3], 0, s[96:97]
	s_mov_b32 m0, s27
	s_add_u32 s8, s6, 0x40080
	global_load_lds_dwordx4 v[2:3], off
	v_lshl_add_u64 v[2:3], v[4:5], 0, s[96:97]
	s_mov_b32 m0, s28
	s_addc_u32 s9, s7, 0
	global_load_lds_dwordx4 v[2:3], off
	s_add_i32 m0, s13, 0x1c000
	v_lshl_add_u64 v[2:3], s[8:9], 0, v[0:1]
	global_load_lds_dwordx4 v[2:3], off
	v_lshl_add_u64 v[2:3], s[8:9], 0, v[150:151]
	s_add_i32 m0, s13, 0x1e000
	v_bfe_u32 v163, v206, 4, 2
	global_load_lds_dwordx4 v[2:3], off
	v_and_b32_e32 v162, 15, v206
	v_lshlrev_b32_e32 v2, 4, v163
	v_lshlrev_b32_e32 v3, 2, v206
	v_lshl_or_b32 v2, v162, 6, v2
	v_and_b32_e32 v3, 32, v3
	v_bitop3_b32 v4, v2, s29, v3 bitop3:0xde
	v_bitop3_b32 v164, s33, v2, v3 bitop3:0xf6
	v_lshlrev_b32_e32 v2, 14, v10
	v_and_b32_e32 v2, 0xffff8000, v2
	v_lshl_add_u32 v2, v11, 11, v2
	v_and_b32_e32 v3, 1, v10
	v_lshl_or_b32 v2, v3, 6, v2
	v_lshl_add_u32 v152, v12, 1, v2
	v_lshlrev_b32_e32 v2, 14, v13
	v_and_b32_e32 v2, 0xffff8000, v2
	s_waitcnt vmcnt(6)
	v_lshl_add_u32 v2, v14, 11, v2
	v_and_b32_e32 v3, 1, v13
	s_cmpk_lt_u32 s1, 0x100
	v_lshl_or_b32 v2, v3, 6, v2
	s_sext_i32_i16 s2, s10
	s_mov_b32 s10, 0
	s_cselect_b64 s[44:45], -1, 0
	s_ashr_i32 s29, s85, 31
	s_ashr_i32 s52, s84, 31
	s_mov_b32 s1, s31
	s_lshr_b32 s53, s0, 3
	v_mov_b32_e32 v153, v1
	v_lshl_add_u32 v154, v15, 1, v2
	v_mov_b32_e32 v155, v1
	v_add_u32_e32 v165, 0, v4
	s_lshl_b32 s54, s26, 2
	s_mov_b64 s[48:49], s[4:5]
	s_mov_b64 s[50:51], s[6:7]
	s_barrier
	s_branch .LBB0_822
